# SwiGLU epilogues (FFN1 and FFN2 gate-up): 15 percent fewer VALU instructions per row (exp argument from one packed multiply, packed add, products reassociated; all f32)
# speedup vs baseline: 1.0038x; 1.0038x over previous
; __device__ __forceinline__ unsigned cvt_pk_bf16(float lo, float hi) { cvf32x2_t v = {lo, hi}; cvbf16x2_t b = __builtin_convertvector(v, cvbf16x2_t); return __builtin_bit_cast(unsigned, b); }
; __device__ __forceinline__ float fsigm(float x) { return __builtin_amdgcn_rcpf(1.f + __expf(-x)); }
; __device__ __forceinline__ float fsilu(float x) { return x * fsigm(x); }
; __device__ __forceinline__ float row_rs(const float* ssq, int row) { return ssq ? rsqrtf(ssq[row] * (1.f / 1024.f) + RMS_EPS) : 1.f; }
;     __device__ __forceinline__ void operator()(const f32x4 (&acc)[2][2][4][2], const Unit& u, int wr, int wc, int fr, int fq) const {
;     ...
;             for (int m = 0; m < 4; ++m) { const int row = row0 + ai * HALF + m * 16; const float rs = row_rs(ssq, row);
;                 u32x4 w; unsigned pk[4];
; #pragma unroll
;                 for (int n = 0; n < 2; ++n) { const f32x4 g = acc[ai][0][m][n] * rs, up = acc[ai][1][m][n] * rs;
;                     pk[2 * n] = cvt_pk_bf16(fsilu(g[0]) * up[0], fsilu(g[1]) * up[1]); pk[2 * n + 1] = cvt_pk_bf16(fsilu(g[2]) * up[2], fsilu(g[3]) * up[3]); }
;                 w.x = pk[0]; w.y = pk[1]; w.z = pk[2]; w.w = pk[3];
;                 st_wt16(H + (size_t)row * ldh + col0, w); }
.LBB0_148:
	v_mul_f32_e32 v184, 0xbfb8aa3b, v152
	v_mul_f32_e32 v186, v152, v152
	v_mov_b32_e32 v188, 1.0
	v_pk_mul_f32 v[180:181], v[124:125], v[184:185] op_sel_hi:[1,0]
	v_pk_mul_f32 v[182:183], v[126:127], v[184:185] op_sel_hi:[1,0]
	v_pk_mul_f32 v[124:125], v[124:125], v[120:121]
	v_exp_f32_e32 v180, v180
	v_exp_f32_e32 v181, v181
	v_exp_f32_e32 v182, v182
	v_exp_f32_e32 v183, v183
	v_pk_mul_f32 v[126:127], v[126:127], v[122:123]
	v_pk_add_f32 v[180:181], v[180:181], v[188:189] op_sel_hi:[1,0]
	v_pk_add_f32 v[182:183], v[182:183], v[188:189] op_sel_hi:[1,0]
	v_rcp_f32_e32 v180, v180
	v_rcp_f32_e32 v181, v181
	v_rcp_f32_e32 v182, v182
	v_rcp_f32_e32 v183, v183
	v_pk_mul_f32 v[124:125], v[124:125], v[186:187] op_sel_hi:[1,0]
	v_pk_mul_f32 v[126:127], v[126:127], v[186:187] op_sel_hi:[1,0]
	v_pk_mul_f32 v[124:125], v[124:125], v[180:181]
	v_pk_mul_f32 v[126:127], v[126:127], v[182:183]
	v_pk_mul_f32 v[180:181], v[116:117], v[184:185] op_sel_hi:[1,0]
	v_pk_mul_f32 v[182:183], v[118:119], v[184:185] op_sel_hi:[1,0]
	v_pk_mul_f32 v[116:117], v[116:117], v[112:113]
	v_exp_f32_e32 v180, v180
	v_exp_f32_e32 v181, v181
	v_exp_f32_e32 v182, v182
	v_exp_f32_e32 v183, v183
	v_pk_mul_f32 v[118:119], v[118:119], v[114:115]
	v_pk_add_f32 v[180:181], v[180:181], v[188:189] op_sel_hi:[1,0]
	v_pk_add_f32 v[182:183], v[182:183], v[188:189] op_sel_hi:[1,0]
	v_rcp_f32_e32 v180, v180
	v_rcp_f32_e32 v181, v181
	v_rcp_f32_e32 v182, v182
	v_rcp_f32_e32 v183, v183
	v_pk_mul_f32 v[116:117], v[116:117], v[186:187] op_sel_hi:[1,0]
	v_pk_mul_f32 v[118:119], v[118:119], v[186:187] op_sel_hi:[1,0]
	v_pk_mul_f32 v[116:117], v[116:117], v[180:181]
	v_pk_mul_f32 v[118:119], v[118:119], v[182:183]
	v_cvt_pk_bf16_f32 v120, v124, v125
	v_cvt_pk_bf16_f32 v121, v126, v127
	v_cvt_pk_bf16_f32 v122, v116, v117
	v_cvt_pk_bf16_f32 v123, v118, v119
	v_lshl_or_b32 v144, s36, 7, v162
	v_ashrrev_i32_e32 v145, 31, v144
	s_and_b64 vcc, exec, s[6:7]
	v_mov_b64_e32 v[112:113], s[56:57]
	v_mad_i64_i32 v[112:113], s[38:39], v146, s81, v[112:113]
	v_lshl_add_u64 v[112:113], v[144:145], 1, v[112:113]
	s_nop 0
	global_store_dwordx4 v[112:113], v[120:123], off
	s_cbranch_vccnz .LBB0_150
	v_fmamk_f32 v112, v173, 0x3a800000, v166
	v_mul_f32_e32 v113, 0x4b800000, v112
	v_cmp_gt_f32_e32 vcc, s80, v112
	s_nop 1
	v_cndmask_b32_e32 v112, v112, v113, vcc
	v_rsq_f32_e32 v112, v112
	s_nop 0
	v_mul_f32_e32 v113, 0x45800000, v112
	v_cndmask_b32_e32 v150, v112, v113, vcc
.LBB0_150:
	v_mul_f32_e32 v184, 0xbfb8aa3b, v150
	v_mul_f32_e32 v186, v150, v150
	v_pk_mul_f32 v[180:181], v[108:109], v[184:185] op_sel_hi:[1,0]
	v_pk_mul_f32 v[182:183], v[110:111], v[184:185] op_sel_hi:[1,0]
	v_pk_mul_f32 v[108:109], v[108:109], v[104:105]
	v_exp_f32_e32 v180, v180
	v_exp_f32_e32 v181, v181
	v_exp_f32_e32 v182, v182
	v_exp_f32_e32 v183, v183
	v_pk_mul_f32 v[110:111], v[110:111], v[106:107]
	v_pk_add_f32 v[180:181], v[180:181], v[188:189] op_sel_hi:[1,0]
	v_pk_add_f32 v[182:183], v[182:183], v[188:189] op_sel_hi:[1,0]
	v_rcp_f32_e32 v180, v180
	v_rcp_f32_e32 v181, v181
	v_rcp_f32_e32 v182, v182
	v_rcp_f32_e32 v183, v183
	v_pk_mul_f32 v[108:109], v[108:109], v[186:187] op_sel_hi:[1,0]
	v_pk_mul_f32 v[110:111], v[110:111], v[186:187] op_sel_hi:[1,0]
	v_pk_mul_f32 v[108:109], v[108:109], v[180:181]
	v_pk_mul_f32 v[110:111], v[110:111], v[182:183]
	v_pk_mul_f32 v[180:181], v[100:101], v[184:185] op_sel_hi:[1,0]
	v_pk_mul_f32 v[182:183], v[102:103], v[184:185] op_sel_hi:[1,0]
	v_pk_mul_f32 v[100:101], v[100:101], v[96:97]
	v_exp_f32_e32 v180, v180
	v_exp_f32_e32 v181, v181
	v_exp_f32_e32 v182, v182
	v_exp_f32_e32 v183, v183
	v_pk_mul_f32 v[102:103], v[102:103], v[98:99]
	v_pk_add_f32 v[180:181], v[180:181], v[188:189] op_sel_hi:[1,0]
	v_pk_add_f32 v[182:183], v[182:183], v[188:189] op_sel_hi:[1,0]
	v_rcp_f32_e32 v180, v180
	v_rcp_f32_e32 v181, v181
	v_rcp_f32_e32 v182, v182
	v_rcp_f32_e32 v183, v183
	v_pk_mul_f32 v[100:101], v[100:101], v[186:187] op_sel_hi:[1,0]
	v_pk_mul_f32 v[102:103], v[102:103], v[186:187] op_sel_hi:[1,0]
	v_pk_mul_f32 v[100:101], v[100:101], v[180:181]
	v_pk_mul_f32 v[102:103], v[102:103], v[182:183]
	v_cvt_pk_bf16_f32 v106, v108, v109
	v_cvt_pk_bf16_f32 v107, v110, v111
	v_cvt_pk_bf16_f32 v108, v100, v101
	v_cvt_pk_bf16_f32 v109, v102, v103
	v_or_b32_e32 v118, 16, v146
	v_mov_b32_e32 v104, 1.0
	s_and_b64 vcc, exec, s[6:7]
	v_mov_b64_e32 v[96:97], s[56:57]
	v_mad_i64_i32 v[96:97], s[38:39], v118, s81, v[96:97]
	v_lshl_add_u64 v[96:97], v[144:145], 1, v[96:97]
	s_nop 0
	global_store_dwordx4 v[96:97], v[106:109], off
	v_mov_b32_e32 v96, 1.0
	s_cbranch_vccnz .LBB0_152
	v_fmamk_f32 v96, v174, 0x3a800000, v166
	v_mul_f32_e32 v97, 0x4b800000, v96
	v_cmp_gt_f32_e32 vcc, s80, v96
	s_nop 1
	v_cndmask_b32_e32 v96, v96, v97, vcc
	v_rsq_f32_e32 v96, v96
	s_nop 0
	v_mul_f32_e32 v97, 0x45800000, v96
	v_cndmask_b32_e32 v96, v96, v97, vcc
; __device__ __forceinline__ unsigned cvt_pk_bf16(float lo, float hi) { cvf32x2_t v = {lo, hi}; cvbf16x2_t b = __builtin_convertvector(v, cvbf16x2_t); return __builtin_bit_cast(unsigned, b); }
; __device__ __forceinline__ float fsigm(float x) { return __builtin_amdgcn_rcpf(1.f + __expf(-x)); }
; __device__ __forceinline__ float fsilu(float x) { return x * fsigm(x); }
; __device__ __forceinline__ float row_rs(const float* ssq, int row) { return ssq ? rsqrtf(ssq[row] * (1.f / 1024.f) + RMS_EPS) : 1.f; }
;     __device__ __forceinline__ void operator()(const f32x4 (&acc)[2][2][4][2], const Unit& u, int wr, int wc, int fr, int fq) const {
;     ...
;             for (int m = 0; m < 4; ++m) { const int row = row0 + ai * HALF + m * 16; const float rs = row_rs(ssq, row);
;                 u32x4 w; unsigned pk[4];
; #pragma unroll
;                 for (int n = 0; n < 2; ++n) { const f32x4 g = acc[ai][0][m][n] * rs, up = acc[ai][1][m][n] * rs;
;                     pk[2 * n] = cvt_pk_bf16(fsilu(g[0]) * up[0], fsilu(g[1]) * up[1]); pk[2 * n + 1] = cvt_pk_bf16(fsilu(g[2]) * up[2], fsilu(g[3]) * up[3]); }
;                 w.x = pk[0]; w.y = pk[1]; w.z = pk[2]; w.w = pk[3];
;                 st_wt16(H + (size_t)row * ldh + col0, w); }
.LBB0_152:
	v_mul_f32_e32 v184, 0xbfb8aa3b, v96
	v_mul_f32_e32 v186, v96, v96
	v_pk_mul_f32 v[180:181], v[92:93], v[184:185] op_sel_hi:[1,0]
	v_pk_mul_f32 v[182:183], v[94:95], v[184:185] op_sel_hi:[1,0]
	v_pk_mul_f32 v[92:93], v[92:93], v[88:89]
	v_exp_f32_e32 v180, v180
	v_exp_f32_e32 v181, v181
	v_exp_f32_e32 v182, v182
	v_exp_f32_e32 v183, v183
	v_pk_mul_f32 v[94:95], v[94:95], v[90:91]
	v_pk_add_f32 v[180:181], v[180:181], v[188:189] op_sel_hi:[1,0]
	v_pk_add_f32 v[182:183], v[182:183], v[188:189] op_sel_hi:[1,0]
	v_rcp_f32_e32 v180, v180
	v_rcp_f32_e32 v181, v181
	v_rcp_f32_e32 v182, v182
	v_rcp_f32_e32 v183, v183
	v_pk_mul_f32 v[92:93], v[92:93], v[186:187] op_sel_hi:[1,0]
	v_pk_mul_f32 v[94:95], v[94:95], v[186:187] op_sel_hi:[1,0]
	v_pk_mul_f32 v[92:93], v[92:93], v[180:181]
	v_pk_mul_f32 v[94:95], v[94:95], v[182:183]
	v_pk_mul_f32 v[180:181], v[84:85], v[184:185] op_sel_hi:[1,0]
	v_pk_mul_f32 v[182:183], v[86:87], v[184:185] op_sel_hi:[1,0]
	v_pk_mul_f32 v[84:85], v[84:85], v[80:81]
	v_exp_f32_e32 v180, v180
	v_exp_f32_e32 v181, v181
	v_exp_f32_e32 v182, v182
	v_exp_f32_e32 v183, v183
	v_pk_mul_f32 v[86:87], v[86:87], v[82:83]
	v_pk_add_f32 v[180:181], v[180:181], v[188:189] op_sel_hi:[1,0]
	v_pk_add_f32 v[182:183], v[182:183], v[188:189] op_sel_hi:[1,0]
	v_rcp_f32_e32 v180, v180
	v_rcp_f32_e32 v181, v181
	v_rcp_f32_e32 v182, v182
	v_rcp_f32_e32 v183, v183
	v_pk_mul_f32 v[84:85], v[84:85], v[186:187] op_sel_hi:[1,0]
	v_pk_mul_f32 v[86:87], v[86:87], v[186:187] op_sel_hi:[1,0]
	v_pk_mul_f32 v[84:85], v[84:85], v[180:181]
	v_pk_mul_f32 v[86:87], v[86:87], v[182:183]
	v_cvt_pk_bf16_f32 v88, v92, v93
	v_cvt_pk_bf16_f32 v89, v94, v95
	v_cvt_pk_bf16_f32 v90, v84, v85
	v_cvt_pk_bf16_f32 v91, v86, v87
	v_or_b32_e32 v97, 32, v146
	s_and_b64 vcc, exec, s[6:7]
	v_mov_b64_e32 v[80:81], s[56:57]
	v_mad_i64_i32 v[80:81], s[38:39], v97, s81, v[80:81]
	v_lshl_add_u64 v[80:81], v[144:145], 1, v[80:81]
	s_nop 0
	global_store_dwordx4 v[80:81], v[88:91], off
	s_cbranch_vccnz .LBB0_154
	v_fmamk_f32 v80, v175, 0x3a800000, v166
	v_mul_f32_e32 v81, 0x4b800000, v80
	v_cmp_gt_f32_e32 vcc, s80, v80
	s_nop 1
	v_cndmask_b32_e32 v80, v80, v81, vcc
	v_rsq_f32_e32 v80, v80
	s_nop 0
	v_mul_f32_e32 v81, 0x45800000, v80
	v_cndmask_b32_e32 v104, v80, v81, vcc
.LBB0_154:
	v_mul_f32_e32 v184, 0xbfb8aa3b, v104
	v_mul_f32_e32 v186, v104, v104
	v_pk_mul_f32 v[180:181], v[76:77], v[184:185] op_sel_hi:[1,0]
	v_pk_mul_f32 v[182:183], v[78:79], v[184:185] op_sel_hi:[1,0]
	v_pk_mul_f32 v[76:77], v[76:77], v[72:73]
	v_exp_f32_e32 v180, v180
	v_exp_f32_e32 v181, v181
	v_exp_f32_e32 v182, v182
	v_exp_f32_e32 v183, v183
	v_pk_mul_f32 v[78:79], v[78:79], v[74:75]
	v_pk_add_f32 v[180:181], v[180:181], v[188:189] op_sel_hi:[1,0]
	v_pk_add_f32 v[182:183], v[182:183], v[188:189] op_sel_hi:[1,0]
	v_rcp_f32_e32 v180, v180
	v_rcp_f32_e32 v181, v181
	v_rcp_f32_e32 v182, v182
	v_rcp_f32_e32 v183, v183
	v_pk_mul_f32 v[76:77], v[76:77], v[186:187] op_sel_hi:[1,0]
	v_pk_mul_f32 v[78:79], v[78:79], v[186:187] op_sel_hi:[1,0]
	v_pk_mul_f32 v[76:77], v[76:77], v[180:181]
	v_pk_mul_f32 v[78:79], v[78:79], v[182:183]
	v_pk_mul_f32 v[180:181], v[68:69], v[184:185] op_sel_hi:[1,0]
	v_pk_mul_f32 v[182:183], v[70:71], v[184:185] op_sel_hi:[1,0]
	v_pk_mul_f32 v[68:69], v[68:69], v[64:65]
	v_exp_f32_e32 v180, v180
	v_exp_f32_e32 v181, v181
	v_exp_f32_e32 v182, v182
	v_exp_f32_e32 v183, v183
	v_pk_mul_f32 v[70:71], v[70:71], v[66:67]
	v_pk_add_f32 v[180:181], v[180:181], v[188:189] op_sel_hi:[1,0]
	v_pk_add_f32 v[182:183], v[182:183], v[188:189] op_sel_hi:[1,0]
	v_rcp_f32_e32 v180, v180
	v_rcp_f32_e32 v181, v181
	v_rcp_f32_e32 v182, v182
	v_rcp_f32_e32 v183, v183
	v_pk_mul_f32 v[68:69], v[68:69], v[186:187] op_sel_hi:[1,0]
	v_pk_mul_f32 v[70:71], v[70:71], v[186:187] op_sel_hi:[1,0]
	v_pk_mul_f32 v[68:69], v[68:69], v[180:181]
	v_pk_mul_f32 v[70:71], v[70:71], v[182:183]
	v_cvt_pk_bf16_f32 v74, v76, v77
	v_cvt_pk_bf16_f32 v75, v78, v79
	v_cvt_pk_bf16_f32 v76, v68, v69
	v_cvt_pk_bf16_f32 v77, v70, v71
	v_or_b32_e32 v86, 48, v146
	v_mov_b32_e32 v72, 1.0
	s_and_b64 vcc, exec, s[6:7]
	v_mov_b64_e32 v[64:65], s[56:57]
	v_mad_i64_i32 v[64:65], s[38:39], v86, s81, v[64:65]
	v_lshl_add_u64 v[64:65], v[144:145], 1, v[64:65]
	s_nop 0
	global_store_dwordx4 v[64:65], v[74:77], off
	v_mov_b32_e32 v64, 1.0
	s_cbranch_vccnz .LBB0_156
	v_fmamk_f32 v64, v176, 0x3a800000, v166
	v_mul_f32_e32 v65, 0x4b800000, v64
	v_cmp_gt_f32_e32 vcc, s80, v64
	s_nop 1
	v_cndmask_b32_e32 v64, v64, v65, vcc
	v_rsq_f32_e32 v64, v64
	s_nop 0
	v_mul_f32_e32 v65, 0x45800000, v64
	v_cndmask_b32_e32 v64, v64, v65, vcc
; __device__ __forceinline__ unsigned cvt_pk_bf16(float lo, float hi) { cvf32x2_t v = {lo, hi}; cvbf16x2_t b = __builtin_convertvector(v, cvbf16x2_t); return __builtin_bit_cast(unsigned, b); }
; __device__ __forceinline__ float fsigm(float x) { return __builtin_amdgcn_rcpf(1.f + __expf(-x)); }
; __device__ __forceinline__ float fsilu(float x) { return x * fsigm(x); }
; __device__ __forceinline__ float row_rs(const float* ssq, int row) { return ssq ? rsqrtf(ssq[row] * (1.f / 1024.f) + RMS_EPS) : 1.f; }
;     __device__ __forceinline__ void operator()(const f32x4 (&acc)[2][2][4][2], const Unit& u, int wr, int wc, int fr, int fq) const {
;     ...
;             for (int m = 0; m < 4; ++m) { const int row = row0 + ai * HALF + m * 16; const float rs = row_rs(ssq, row);
;                 u32x4 w; unsigned pk[4];
; #pragma unroll
;                 for (int n = 0; n < 2; ++n) { const f32x4 g = acc[ai][0][m][n] * rs, up = acc[ai][1][m][n] * rs;
;                     pk[2 * n] = cvt_pk_bf16(fsilu(g[0]) * up[0], fsilu(g[1]) * up[1]); pk[2 * n + 1] = cvt_pk_bf16(fsilu(g[2]) * up[2], fsilu(g[3]) * up[3]); }
;                 w.x = pk[0]; w.y = pk[1]; w.z = pk[2]; w.w = pk[3];
;                 st_wt16(H + (size_t)row * ldh + col0, w); }
.LBB0_156:
	v_mul_f32_e32 v184, 0xbfb8aa3b, v64
	v_mul_f32_e32 v186, v64, v64
	v_pk_mul_f32 v[180:181], v[60:61], v[184:185] op_sel_hi:[1,0]
	v_pk_mul_f32 v[182:183], v[62:63], v[184:185] op_sel_hi:[1,0]
	v_pk_mul_f32 v[60:61], v[60:61], v[56:57]
	v_exp_f32_e32 v180, v180
	v_exp_f32_e32 v181, v181
	v_exp_f32_e32 v182, v182
	v_exp_f32_e32 v183, v183
	v_pk_mul_f32 v[62:63], v[62:63], v[58:59]
	v_pk_add_f32 v[180:181], v[180:181], v[188:189] op_sel_hi:[1,0]
	v_pk_add_f32 v[182:183], v[182:183], v[188:189] op_sel_hi:[1,0]
	v_rcp_f32_e32 v180, v180
	v_rcp_f32_e32 v181, v181
	v_rcp_f32_e32 v182, v182
	v_rcp_f32_e32 v183, v183
	v_pk_mul_f32 v[60:61], v[60:61], v[186:187] op_sel_hi:[1,0]
	v_pk_mul_f32 v[62:63], v[62:63], v[186:187] op_sel_hi:[1,0]
	v_pk_mul_f32 v[60:61], v[60:61], v[180:181]
	v_pk_mul_f32 v[62:63], v[62:63], v[182:183]
	v_pk_mul_f32 v[180:181], v[52:53], v[184:185] op_sel_hi:[1,0]
	v_pk_mul_f32 v[182:183], v[54:55], v[184:185] op_sel_hi:[1,0]
	v_pk_mul_f32 v[52:53], v[52:53], v[48:49]
	v_exp_f32_e32 v180, v180
	v_exp_f32_e32 v181, v181
	v_exp_f32_e32 v182, v182
	v_exp_f32_e32 v183, v183
	v_pk_mul_f32 v[54:55], v[54:55], v[50:51]
	v_pk_add_f32 v[180:181], v[180:181], v[188:189] op_sel_hi:[1,0]
	v_pk_add_f32 v[182:183], v[182:183], v[188:189] op_sel_hi:[1,0]
	v_rcp_f32_e32 v180, v180
	v_rcp_f32_e32 v181, v181
	v_rcp_f32_e32 v182, v182
	v_rcp_f32_e32 v183, v183
	v_pk_mul_f32 v[52:53], v[52:53], v[186:187] op_sel_hi:[1,0]
	v_pk_mul_f32 v[54:55], v[54:55], v[186:187] op_sel_hi:[1,0]
	v_pk_mul_f32 v[52:53], v[52:53], v[180:181]
	v_pk_mul_f32 v[54:55], v[54:55], v[182:183]
	v_cvt_pk_bf16_f32 v56, v60, v61
	v_cvt_pk_bf16_f32 v57, v62, v63
	v_cvt_pk_bf16_f32 v58, v52, v53
	v_cvt_pk_bf16_f32 v59, v54, v55
	v_add_u32_e32 v65, 0x80, v146
	s_and_b64 vcc, exec, s[6:7]
	v_mov_b64_e32 v[48:49], s[56:57]
	v_mad_i64_i32 v[48:49], s[38:39], v65, s81, v[48:49]
	v_lshl_add_u64 v[48:49], v[144:145], 1, v[48:49]
	s_nop 0
	global_store_dwordx4 v[48:49], v[56:59], off
	s_cbranch_vccnz .LBB0_158
	v_fmamk_f32 v48, v177, 0x3a800000, v166
	v_mul_f32_e32 v49, 0x4b800000, v48
	v_cmp_gt_f32_e32 vcc, s80, v48
	s_nop 1
	v_cndmask_b32_e32 v48, v48, v49, vcc
	v_rsq_f32_e32 v48, v48
	s_nop 0
	v_mul_f32_e32 v49, 0x45800000, v48
	v_cndmask_b32_e32 v72, v48, v49, vcc
.LBB0_158:
	v_mul_f32_e32 v184, 0xbfb8aa3b, v72
	v_mul_f32_e32 v186, v72, v72
	v_pk_mul_f32 v[180:181], v[44:45], v[184:185] op_sel_hi:[1,0]
	v_pk_mul_f32 v[182:183], v[46:47], v[184:185] op_sel_hi:[1,0]
	v_pk_mul_f32 v[44:45], v[44:45], v[40:41]
	v_exp_f32_e32 v180, v180
	v_exp_f32_e32 v181, v181
	v_exp_f32_e32 v182, v182
	v_exp_f32_e32 v183, v183
	v_pk_mul_f32 v[46:47], v[46:47], v[42:43]
	v_pk_add_f32 v[180:181], v[180:181], v[188:189] op_sel_hi:[1,0]
	v_pk_add_f32 v[182:183], v[182:183], v[188:189] op_sel_hi:[1,0]
	v_rcp_f32_e32 v180, v180
	v_rcp_f32_e32 v181, v181
	v_rcp_f32_e32 v182, v182
	v_rcp_f32_e32 v183, v183
	v_pk_mul_f32 v[44:45], v[44:45], v[186:187] op_sel_hi:[1,0]
	v_pk_mul_f32 v[46:47], v[46:47], v[186:187] op_sel_hi:[1,0]
	v_pk_mul_f32 v[44:45], v[44:45], v[180:181]
	v_pk_mul_f32 v[46:47], v[46:47], v[182:183]
	v_pk_mul_f32 v[180:181], v[36:37], v[184:185] op_sel_hi:[1,0]
	v_pk_mul_f32 v[182:183], v[38:39], v[184:185] op_sel_hi:[1,0]
	v_pk_mul_f32 v[36:37], v[36:37], v[32:33]
	v_exp_f32_e32 v180, v180
	v_exp_f32_e32 v181, v181
	v_exp_f32_e32 v182, v182
	v_exp_f32_e32 v183, v183
	v_pk_mul_f32 v[38:39], v[38:39], v[34:35]
	v_pk_add_f32 v[180:181], v[180:181], v[188:189] op_sel_hi:[1,0]
	v_pk_add_f32 v[182:183], v[182:183], v[188:189] op_sel_hi:[1,0]
	v_rcp_f32_e32 v180, v180
	v_rcp_f32_e32 v181, v181
	v_rcp_f32_e32 v182, v182
	v_rcp_f32_e32 v183, v183
	v_pk_mul_f32 v[36:37], v[36:37], v[186:187] op_sel_hi:[1,0]
	v_pk_mul_f32 v[38:39], v[38:39], v[186:187] op_sel_hi:[1,0]
	v_pk_mul_f32 v[36:37], v[36:37], v[180:181]
	v_pk_mul_f32 v[38:39], v[38:39], v[182:183]
	v_cvt_pk_bf16_f32 v42, v44, v45
	v_cvt_pk_bf16_f32 v43, v46, v47
	v_cvt_pk_bf16_f32 v44, v36, v37
	v_cvt_pk_bf16_f32 v45, v38, v39
	v_add_u32_e32 v54, 0x90, v146
	v_mov_b32_e32 v40, 1.0
	s_and_b64 vcc, exec, s[6:7]
	v_mov_b64_e32 v[32:33], s[56:57]
	v_mad_i64_i32 v[32:33], s[38:39], v54, s81, v[32:33]
	v_lshl_add_u64 v[32:33], v[144:145], 1, v[32:33]
	s_nop 0
	global_store_dwordx4 v[32:33], v[42:45], off
	v_mov_b32_e32 v32, 1.0
	s_cbranch_vccnz .LBB0_160
	v_fmamk_f32 v32, v178, 0x3a800000, v166
	v_mul_f32_e32 v33, 0x4b800000, v32
	v_cmp_gt_f32_e32 vcc, s80, v32
	s_nop 1
	v_cndmask_b32_e32 v32, v32, v33, vcc
	v_rsq_f32_e32 v32, v32
	s_nop 0
	v_mul_f32_e32 v33, 0x45800000, v32
	v_cndmask_b32_e32 v32, v32, v33, vcc
; __device__ __forceinline__ unsigned cvt_pk_bf16(float lo, float hi) { cvf32x2_t v = {lo, hi}; cvbf16x2_t b = __builtin_convertvector(v, cvbf16x2_t); return __builtin_bit_cast(unsigned, b); }
; #define PG8_BAR __builtin_amdgcn_s_barrier()
; template <class Epi, class Sched, bool ALIGN_EPI = false, bool SP2 = false>
; __device__ __forceinline__ void gemm_phase(PG8_LAS unsigned char* lds, const Gemm g, const Sched& S, const Epi& E) {
;     ...
;                     for (int n = 0; n < 2; ++n) acc[a][b][m][n] = (f32x4){0.f, 0.f, 0.f, 0.f};
;         cur = nxt; cA = nA; cB = nB; ++ui;
;         if constexpr (ALIGN_EPI) { if (wr == 1) PG8_BAR; }
; __device__ __forceinline__ float fsigm(float x) { return __builtin_amdgcn_rcpf(1.f + __expf(-x)); }
; __device__ __forceinline__ float fsilu(float x) { return x * fsigm(x); }
; __device__ __forceinline__ float row_rs(const float* ssq, int row) { return ssq ? rsqrtf(ssq[row] * (1.f / 1024.f) + RMS_EPS) : 1.f; }
;     __device__ __forceinline__ void operator()(const f32x4 (&acc)[2][2][4][2], const Unit& u, int wr, int wc, int fr, int fq) const {
;     ...
;             for (int m = 0; m < 4; ++m) { const int row = row0 + ai * HALF + m * 16; const float rs = row_rs(ssq, row);
;                 u32x4 w; unsigned pk[4];
; #pragma unroll
;                 for (int n = 0; n < 2; ++n) { const f32x4 g = acc[ai][0][m][n] * rs, up = acc[ai][1][m][n] * rs;
;                     pk[2 * n] = cvt_pk_bf16(fsilu(g[0]) * up[0], fsilu(g[1]) * up[1]); pk[2 * n + 1] = cvt_pk_bf16(fsilu(g[2]) * up[2], fsilu(g[3]) * up[3]); }
;                 w.x = pk[0]; w.y = pk[1]; w.z = pk[2]; w.w = pk[3];
;                 st_wt16(H + (size_t)row * ldh + col0, w); }
.LBB0_160:
	v_mul_f32_e32 v184, 0xbfb8aa3b, v32
	v_mul_f32_e32 v186, v32, v32
	v_pk_mul_f32 v[180:181], v[28:29], v[184:185] op_sel_hi:[1,0]
	v_pk_mul_f32 v[182:183], v[30:31], v[184:185] op_sel_hi:[1,0]
	v_pk_mul_f32 v[28:29], v[28:29], v[24:25]
	v_exp_f32_e32 v180, v180
	v_exp_f32_e32 v181, v181
	v_exp_f32_e32 v182, v182
	v_exp_f32_e32 v183, v183
	v_pk_mul_f32 v[30:31], v[30:31], v[26:27]
	v_pk_add_f32 v[180:181], v[180:181], v[188:189] op_sel_hi:[1,0]
	v_pk_add_f32 v[182:183], v[182:183], v[188:189] op_sel_hi:[1,0]
	v_rcp_f32_e32 v180, v180
	v_rcp_f32_e32 v181, v181
	v_rcp_f32_e32 v182, v182
	v_rcp_f32_e32 v183, v183
	v_pk_mul_f32 v[28:29], v[28:29], v[186:187] op_sel_hi:[1,0]
	v_pk_mul_f32 v[30:31], v[30:31], v[186:187] op_sel_hi:[1,0]
	v_pk_mul_f32 v[28:29], v[28:29], v[180:181]
	v_pk_mul_f32 v[30:31], v[30:31], v[182:183]
	v_pk_mul_f32 v[180:181], v[20:21], v[184:185] op_sel_hi:[1,0]
	v_pk_mul_f32 v[182:183], v[22:23], v[184:185] op_sel_hi:[1,0]
	v_pk_mul_f32 v[20:21], v[20:21], v[16:17]
	v_exp_f32_e32 v180, v180
	v_exp_f32_e32 v181, v181
	v_exp_f32_e32 v182, v182
	v_exp_f32_e32 v183, v183
	v_pk_mul_f32 v[22:23], v[22:23], v[18:19]
	v_pk_add_f32 v[180:181], v[180:181], v[188:189] op_sel_hi:[1,0]
	v_pk_add_f32 v[182:183], v[182:183], v[188:189] op_sel_hi:[1,0]
	v_rcp_f32_e32 v180, v180
	v_rcp_f32_e32 v181, v181
	v_rcp_f32_e32 v182, v182
	v_rcp_f32_e32 v183, v183
	v_pk_mul_f32 v[20:21], v[20:21], v[186:187] op_sel_hi:[1,0]
	v_pk_mul_f32 v[22:23], v[22:23], v[186:187] op_sel_hi:[1,0]
	v_pk_mul_f32 v[20:21], v[20:21], v[180:181]
	v_pk_mul_f32 v[22:23], v[22:23], v[182:183]
	v_cvt_pk_bf16_f32 v24, v28, v29
	v_cvt_pk_bf16_f32 v25, v30, v31
	v_cvt_pk_bf16_f32 v26, v20, v21
	v_cvt_pk_bf16_f32 v27, v22, v23
	v_add_u32_e32 v33, 0xa0, v146
	s_and_b64 vcc, exec, s[6:7]
	v_mov_b64_e32 v[16:17], s[56:57]
	v_mad_i64_i32 v[16:17], s[38:39], v33, s81, v[16:17]
	v_lshl_add_u64 v[16:17], v[144:145], 1, v[16:17]
	s_nop 0
	global_store_dwordx4 v[16:17], v[24:27], off
	s_cbranch_vccnz .LBB0_162
	v_fmamk_f32 v16, v179, 0x3a800000, v166
	v_mul_f32_e32 v17, 0x4b800000, v16
	v_cmp_gt_f32_e32 vcc, s80, v16
	s_nop 1
	v_cndmask_b32_e32 v16, v16, v17, vcc
	v_rsq_f32_e32 v16, v16
	s_nop 0
	v_mul_f32_e32 v17, 0x45800000, v16
	v_cndmask_b32_e32 v40, v16, v17, vcc
.LBB0_162:
	v_mul_f32_e32 v184, 0xbfb8aa3b, v40
	v_mul_f32_e32 v186, v40, v40
	v_pk_mul_f32 v[180:181], v[12:13], v[184:185] op_sel_hi:[1,0]
	v_pk_mul_f32 v[182:183], v[14:15], v[184:185] op_sel_hi:[1,0]
	v_pk_mul_f32 v[12:13], v[12:13], v[8:9]
	v_exp_f32_e32 v180, v180
	v_exp_f32_e32 v181, v181
	v_exp_f32_e32 v182, v182
	v_exp_f32_e32 v183, v183
	v_pk_mul_f32 v[14:15], v[14:15], v[10:11]
	v_pk_add_f32 v[180:181], v[180:181], v[188:189] op_sel_hi:[1,0]
	v_pk_add_f32 v[182:183], v[182:183], v[188:189] op_sel_hi:[1,0]
	v_rcp_f32_e32 v180, v180
	v_rcp_f32_e32 v181, v181
	v_rcp_f32_e32 v182, v182
	v_rcp_f32_e32 v183, v183
	v_pk_mul_f32 v[12:13], v[12:13], v[186:187] op_sel_hi:[1,0]
	v_pk_mul_f32 v[14:15], v[14:15], v[186:187] op_sel_hi:[1,0]
	v_pk_mul_f32 v[12:13], v[12:13], v[180:181]
	v_pk_mul_f32 v[14:15], v[14:15], v[182:183]
	v_pk_mul_f32 v[180:181], v[4:5], v[184:185] op_sel_hi:[1,0]
	v_pk_mul_f32 v[182:183], v[6:7], v[184:185] op_sel_hi:[1,0]
	v_pk_mul_f32 v[4:5], v[4:5], v[0:1]
	v_exp_f32_e32 v180, v180
	v_exp_f32_e32 v181, v181
	v_exp_f32_e32 v182, v182
	v_exp_f32_e32 v183, v183
	v_pk_mul_f32 v[6:7], v[6:7], v[2:3]
	v_pk_add_f32 v[180:181], v[180:181], v[188:189] op_sel_hi:[1,0]
	v_pk_add_f32 v[182:183], v[182:183], v[188:189] op_sel_hi:[1,0]
	v_rcp_f32_e32 v180, v180
	v_rcp_f32_e32 v181, v181
	v_rcp_f32_e32 v182, v182
	v_rcp_f32_e32 v183, v183
	v_pk_mul_f32 v[4:5], v[4:5], v[186:187] op_sel_hi:[1,0]
	v_pk_mul_f32 v[6:7], v[6:7], v[186:187] op_sel_hi:[1,0]
	v_pk_mul_f32 v[4:5], v[4:5], v[180:181]
	v_pk_mul_f32 v[6:7], v[6:7], v[182:183]
	v_cvt_pk_bf16_f32 v8, v12, v13
	v_cvt_pk_bf16_f32 v9, v14, v15
	v_cvt_pk_bf16_f32 v10, v4, v5
	v_cvt_pk_bf16_f32 v11, v6, v7
	v_add_u32_e32 v20, 0xb0, v146
	s_andn2_b64 vcc, exec, s[4:5]
	s_mov_b64 s[4:5], -1
	v_mov_b64_e32 v[0:1], s[56:57]
	v_mad_i64_i32 v[0:1], s[6:7], v20, s81, v[0:1]
	v_lshl_add_u64 v[0:1], v[144:145], 1, v[0:1]
	s_nop 0
	global_store_dwordx4 v[0:1], v[8:11], off
	s_cbranch_vccnz .LBB0_139
	s_andn2_b64 vcc, exec, s[10:11]
	s_cbranch_vccnz .LBB0_138
	s_barrier
	s_branch .LBB0_138

; __device__ __forceinline__ unsigned cvt_pk_bf16(float lo, float hi) { cvf32x2_t v = {lo, hi}; cvbf16x2_t b = __builtin_convertvector(v, cvbf16x2_t); return __builtin_bit_cast(unsigned, b); }
; __device__ __forceinline__ float fsigm(float x) { return __builtin_amdgcn_rcpf(1.f + __expf(-x)); }
; __device__ __forceinline__ float fsilu(float x) { return x * fsigm(x); }
; __device__ __forceinline__ float row_rs(const float* ssq, int row) { return ssq ? rsqrtf(ssq[row] * (1.f / 1024.f) + RMS_EPS) : 1.f; }
;     __device__ __forceinline__ void operator()(const f32x4 (&acc)[2][2][4][2], const Unit& u, int wr, int wc, int fr, int fq) const {
;     ...
;             for (int m = 0; m < 4; ++m) { const int row = row0 + ai * HALF + m * 16; const float rs = row_rs(ssq, row);
;                 u32x4 w; unsigned pk[4];
; #pragma unroll
;                 for (int n = 0; n < 2; ++n) { const f32x4 g = acc[ai][0][m][n] * rs, up = acc[ai][1][m][n] * rs;
;                     pk[2 * n] = cvt_pk_bf16(fsilu(g[0]) * up[0], fsilu(g[1]) * up[1]); pk[2 * n + 1] = cvt_pk_bf16(fsilu(g[2]) * up[2], fsilu(g[3]) * up[3]); }
;                 w.x = pk[0]; w.y = pk[1]; w.z = pk[2]; w.w = pk[3];
;                 st_wt16(H + (size_t)row * ldh + col0, w); }
.LBB0_1274:
	v_lshl_add_u32 v144, s6, 8, v152
	v_ashrrev_i32_e32 v145, 31, v144
	v_lshl_add_u64 v[150:151], v[144:145], 2, s[12:13]
	global_load_dword v145, v[150:151], off
	v_or_b32_e32 v162, 16, v144
	v_ashrrev_i32_e32 v163, 31, v162
	v_lshl_add_u64 v[164:165], v[162:163], 2, s[12:13]
	v_lshl_or_b32 v148, s7, 7, v154
	v_mov_b64_e32 v[146:147], s[56:57]
	v_ashrrev_i32_e32 v149, 31, v148
	v_mad_i64_i32 v[160:161], s[6:7], v144, s79, v[146:147]
	v_lshlrev_b64 v[148:149], 1, v[148:149]
	v_lshl_add_u64 v[160:161], v[160:161], 0, v[148:149]
	s_waitcnt vmcnt(0)
	v_fmamk_f32 v145, v145, 0x3a800000, v158
	v_mul_f32_e32 v159, 0x4b800000, v145
	v_cmp_gt_f32_e32 vcc, s77, v145
	s_nop 1
	v_cndmask_b32_e32 v145, v145, v159, vcc
	v_rsq_f32_e32 v145, v145
	s_nop 0
	v_mul_f32_e32 v159, 0x45800000, v145
	v_cndmask_b32_e32 v166, v145, v159, vcc
	v_mov_b32_e32 v188, 1.0
	v_mul_f32_e32 v184, 0xbfb8aa3b, v166
	v_mul_f32_e32 v186, v166, v166
	v_pk_mul_f32 v[180:181], v[124:125], v[184:185] op_sel_hi:[1,0]
	v_pk_mul_f32 v[182:183], v[126:127], v[184:185] op_sel_hi:[1,0]
	v_pk_mul_f32 v[124:125], v[124:125], v[116:117]
	v_exp_f32_e32 v180, v180
	v_exp_f32_e32 v181, v181
	v_exp_f32_e32 v182, v182
	v_exp_f32_e32 v183, v183
	v_pk_mul_f32 v[126:127], v[126:127], v[118:119]
	v_pk_add_f32 v[180:181], v[180:181], v[188:189] op_sel_hi:[1,0]
	v_pk_add_f32 v[182:183], v[182:183], v[188:189] op_sel_hi:[1,0]
	v_rcp_f32_e32 v180, v180
	v_rcp_f32_e32 v181, v181
	v_rcp_f32_e32 v182, v182
	v_rcp_f32_e32 v183, v183
	v_pk_mul_f32 v[124:125], v[124:125], v[186:187] op_sel_hi:[1,0]
	v_pk_mul_f32 v[126:127], v[126:127], v[186:187] op_sel_hi:[1,0]
	v_pk_mul_f32 v[124:125], v[124:125], v[180:181]
	v_pk_mul_f32 v[126:127], v[126:127], v[182:183]
	v_pk_mul_f32 v[180:181], v[120:121], v[184:185] op_sel_hi:[1,0]
	v_pk_mul_f32 v[182:183], v[122:123], v[184:185] op_sel_hi:[1,0]
	v_pk_mul_f32 v[120:121], v[120:121], v[112:113]
	v_exp_f32_e32 v180, v180
	v_exp_f32_e32 v181, v181
	v_exp_f32_e32 v182, v182
	v_exp_f32_e32 v183, v183
	v_pk_mul_f32 v[122:123], v[122:123], v[114:115]
	v_pk_add_f32 v[180:181], v[180:181], v[188:189] op_sel_hi:[1,0]
	v_pk_add_f32 v[182:183], v[182:183], v[188:189] op_sel_hi:[1,0]
	v_rcp_f32_e32 v180, v180
	v_rcp_f32_e32 v181, v181
	v_rcp_f32_e32 v182, v182
	v_rcp_f32_e32 v183, v183
	v_pk_mul_f32 v[120:121], v[120:121], v[186:187] op_sel_hi:[1,0]
	v_pk_mul_f32 v[122:123], v[122:123], v[186:187] op_sel_hi:[1,0]
	v_pk_mul_f32 v[120:121], v[120:121], v[180:181]
	v_pk_mul_f32 v[122:123], v[122:123], v[182:183]
	v_cvt_pk_bf16_f32 v112, v124, v125
	v_cvt_pk_bf16_f32 v113, v126, v127
	v_cvt_pk_bf16_f32 v114, v120, v121
	v_cvt_pk_bf16_f32 v115, v122, v123
	s_nop 0
	global_store_dwordx4 v[160:161], v[112:115], off
	global_load_dword v113, v[164:165], off
	s_nop 0
	v_or_b32_e32 v112, 32, v144
	v_mad_i64_i32 v[114:115], s[6:7], v162, s79, v[146:147]
	v_lshl_add_u64 v[114:115], v[114:115], 0, v[148:149]
	s_waitcnt vmcnt(0)
	v_fmamk_f32 v113, v113, 0x3a800000, v158
	v_mul_f32_e32 v116, 0x4b800000, v113
	v_cmp_gt_f32_e32 vcc, s77, v113
	s_nop 1
	v_cndmask_b32_e32 v113, v113, v116, vcc
	v_rsq_f32_e32 v118, v113
	v_ashrrev_i32_e32 v113, 31, v112
	v_lshl_add_u64 v[116:117], v[112:113], 2, s[12:13]
	v_mul_f32_e32 v113, 0x45800000, v118
	v_cndmask_b32_e32 v118, v118, v113, vcc
	v_mul_f32_e32 v184, 0xbfb8aa3b, v118
	v_mul_f32_e32 v186, v118, v118
	v_pk_mul_f32 v[180:181], v[108:109], v[184:185] op_sel_hi:[1,0]
	v_pk_mul_f32 v[182:183], v[110:111], v[184:185] op_sel_hi:[1,0]
	v_pk_mul_f32 v[108:109], v[108:109], v[100:101]
	v_exp_f32_e32 v180, v180
	v_exp_f32_e32 v181, v181
	v_exp_f32_e32 v182, v182
	v_exp_f32_e32 v183, v183
	v_pk_mul_f32 v[110:111], v[110:111], v[102:103]
	v_pk_add_f32 v[180:181], v[180:181], v[188:189] op_sel_hi:[1,0]
	v_pk_add_f32 v[182:183], v[182:183], v[188:189] op_sel_hi:[1,0]
	v_rcp_f32_e32 v180, v180
	v_rcp_f32_e32 v181, v181
	v_rcp_f32_e32 v182, v182
	v_rcp_f32_e32 v183, v183
	v_pk_mul_f32 v[108:109], v[108:109], v[186:187] op_sel_hi:[1,0]
	v_pk_mul_f32 v[110:111], v[110:111], v[186:187] op_sel_hi:[1,0]
	v_pk_mul_f32 v[108:109], v[108:109], v[180:181]
	v_pk_mul_f32 v[110:111], v[110:111], v[182:183]
	v_pk_mul_f32 v[180:181], v[104:105], v[184:185] op_sel_hi:[1,0]
	v_pk_mul_f32 v[182:183], v[106:107], v[184:185] op_sel_hi:[1,0]
	v_pk_mul_f32 v[104:105], v[104:105], v[96:97]
	v_exp_f32_e32 v180, v180
	v_exp_f32_e32 v181, v181
	v_exp_f32_e32 v182, v182
	v_exp_f32_e32 v183, v183
	v_pk_mul_f32 v[106:107], v[106:107], v[98:99]
	v_pk_add_f32 v[180:181], v[180:181], v[188:189] op_sel_hi:[1,0]
	v_pk_add_f32 v[182:183], v[182:183], v[188:189] op_sel_hi:[1,0]
	v_rcp_f32_e32 v180, v180
	v_rcp_f32_e32 v181, v181
	v_rcp_f32_e32 v182, v182
	v_rcp_f32_e32 v183, v183
	v_pk_mul_f32 v[104:105], v[104:105], v[186:187] op_sel_hi:[1,0]
	v_pk_mul_f32 v[106:107], v[106:107], v[186:187] op_sel_hi:[1,0]
	v_pk_mul_f32 v[104:105], v[104:105], v[180:181]
	v_pk_mul_f32 v[106:107], v[106:107], v[182:183]
	v_cvt_pk_bf16_f32 v96, v108, v109
	v_cvt_pk_bf16_f32 v97, v110, v111
	v_cvt_pk_bf16_f32 v98, v104, v105
	v_cvt_pk_bf16_f32 v99, v106, v107
	s_nop 0
	global_store_dwordx4 v[114:115], v[96:99], off
	global_load_dword v97, v[116:117], off
	s_nop 0
	v_or_b32_e32 v96, 48, v144
	v_mad_i64_i32 v[98:99], s[6:7], v112, s79, v[146:147]
	v_lshl_add_u64 v[98:99], v[98:99], 0, v[148:149]
	s_waitcnt vmcnt(0)
; __device__ __forceinline__ unsigned cvt_pk_bf16(float lo, float hi) { cvf32x2_t v = {lo, hi}; cvbf16x2_t b = __builtin_convertvector(v, cvbf16x2_t); return __builtin_bit_cast(unsigned, b); }
; __device__ __forceinline__ float fsigm(float x) { return __builtin_amdgcn_rcpf(1.f + __expf(-x)); }
; __device__ __forceinline__ float fsilu(float x) { return x * fsigm(x); }
; __device__ __forceinline__ float row_rs(const float* ssq, int row) { return ssq ? rsqrtf(ssq[row] * (1.f / 1024.f) + RMS_EPS) : 1.f; }
;     __device__ __forceinline__ void operator()(const f32x4 (&acc)[2][2][4][2], const Unit& u, int wr, int wc, int fr, int fq) const {
;     ...
;             for (int m = 0; m < 4; ++m) { const int row = row0 + ai * HALF + m * 16; const float rs = row_rs(ssq, row);
;                 u32x4 w; unsigned pk[4];
; #pragma unroll
;                 for (int n = 0; n < 2; ++n) { const f32x4 g = acc[ai][0][m][n] * rs, up = acc[ai][1][m][n] * rs;
;                     pk[2 * n] = cvt_pk_bf16(fsilu(g[0]) * up[0], fsilu(g[1]) * up[1]); pk[2 * n + 1] = cvt_pk_bf16(fsilu(g[2]) * up[2], fsilu(g[3]) * up[3]); }
;                 w.x = pk[0]; w.y = pk[1]; w.z = pk[2]; w.w = pk[3];
;                 st_wt16(H + (size_t)row * ldh + col0, w); }
	v_fmamk_f32 v97, v97, 0x3a800000, v158
	v_mul_f32_e32 v100, 0x4b800000, v97
	v_cmp_gt_f32_e32 vcc, s77, v97
	s_nop 1
	v_cndmask_b32_e32 v97, v97, v100, vcc
	v_rsq_f32_e32 v102, v97
	v_ashrrev_i32_e32 v97, 31, v96
	v_lshl_add_u64 v[100:101], v[96:97], 2, s[12:13]
	v_mul_f32_e32 v97, 0x45800000, v102
	v_cndmask_b32_e32 v102, v102, v97, vcc
	v_mul_f32_e32 v184, 0xbfb8aa3b, v102
	v_mul_f32_e32 v186, v102, v102
	v_pk_mul_f32 v[180:181], v[92:93], v[184:185] op_sel_hi:[1,0]
	v_pk_mul_f32 v[182:183], v[94:95], v[184:185] op_sel_hi:[1,0]
	v_pk_mul_f32 v[92:93], v[92:93], v[84:85]
	v_exp_f32_e32 v180, v180
	v_exp_f32_e32 v181, v181
	v_exp_f32_e32 v182, v182
	v_exp_f32_e32 v183, v183
	v_pk_mul_f32 v[94:95], v[94:95], v[86:87]
	v_pk_add_f32 v[180:181], v[180:181], v[188:189] op_sel_hi:[1,0]
	v_pk_add_f32 v[182:183], v[182:183], v[188:189] op_sel_hi:[1,0]
	v_rcp_f32_e32 v180, v180
	v_rcp_f32_e32 v181, v181
	v_rcp_f32_e32 v182, v182
	v_rcp_f32_e32 v183, v183
	v_pk_mul_f32 v[92:93], v[92:93], v[186:187] op_sel_hi:[1,0]
	v_pk_mul_f32 v[94:95], v[94:95], v[186:187] op_sel_hi:[1,0]
	v_pk_mul_f32 v[92:93], v[92:93], v[180:181]
	v_pk_mul_f32 v[94:95], v[94:95], v[182:183]
	v_pk_mul_f32 v[180:181], v[88:89], v[184:185] op_sel_hi:[1,0]
	v_pk_mul_f32 v[182:183], v[90:91], v[184:185] op_sel_hi:[1,0]
	v_pk_mul_f32 v[88:89], v[88:89], v[80:81]
	v_exp_f32_e32 v180, v180
	v_exp_f32_e32 v181, v181
	v_exp_f32_e32 v182, v182
	v_exp_f32_e32 v183, v183
	v_pk_mul_f32 v[90:91], v[90:91], v[82:83]
	v_pk_add_f32 v[180:181], v[180:181], v[188:189] op_sel_hi:[1,0]
	v_pk_add_f32 v[182:183], v[182:183], v[188:189] op_sel_hi:[1,0]
	v_rcp_f32_e32 v180, v180
	v_rcp_f32_e32 v181, v181
	v_rcp_f32_e32 v182, v182
	v_rcp_f32_e32 v183, v183
	v_pk_mul_f32 v[88:89], v[88:89], v[186:187] op_sel_hi:[1,0]
	v_pk_mul_f32 v[90:91], v[90:91], v[186:187] op_sel_hi:[1,0]
	v_pk_mul_f32 v[88:89], v[88:89], v[180:181]
	v_pk_mul_f32 v[90:91], v[90:91], v[182:183]
	v_cvt_pk_bf16_f32 v80, v92, v93
	v_cvt_pk_bf16_f32 v81, v94, v95
	v_cvt_pk_bf16_f32 v82, v88, v89
	v_cvt_pk_bf16_f32 v83, v90, v91
	s_nop 0
	global_store_dwordx4 v[98:99], v[80:83], off
	global_load_dword v80, v[100:101], off
	s_waitcnt vmcnt(0)
	v_fmamk_f32 v80, v80, 0x3a800000, v158
	v_mul_f32_e32 v81, 0x4b800000, v80
	v_cmp_gt_f32_e32 vcc, s77, v80
	s_nop 1
	v_cndmask_b32_e32 v80, v80, v81, vcc
	v_rsq_f32_e32 v82, v80
	v_mad_i64_i32 v[80:81], s[6:7], v96, s79, v[146:147]
	v_lshl_add_u64 v[80:81], v[80:81], 0, v[148:149]
	v_mul_f32_e32 v83, 0x45800000, v82
	v_cndmask_b32_e32 v82, v82, v83, vcc
	v_mul_f32_e32 v184, 0xbfb8aa3b, v82
	v_mul_f32_e32 v186, v82, v82
	v_pk_mul_f32 v[180:181], v[76:77], v[184:185] op_sel_hi:[1,0]
	v_pk_mul_f32 v[182:183], v[78:79], v[184:185] op_sel_hi:[1,0]
	v_pk_mul_f32 v[76:77], v[76:77], v[68:69]
	v_exp_f32_e32 v180, v180
	v_exp_f32_e32 v181, v181
	v_exp_f32_e32 v182, v182
	v_exp_f32_e32 v183, v183
	v_pk_mul_f32 v[78:79], v[78:79], v[70:71]
	v_pk_add_f32 v[180:181], v[180:181], v[188:189] op_sel_hi:[1,0]
	v_pk_add_f32 v[182:183], v[182:183], v[188:189] op_sel_hi:[1,0]
	v_rcp_f32_e32 v180, v180
	v_rcp_f32_e32 v181, v181
	v_rcp_f32_e32 v182, v182
	v_rcp_f32_e32 v183, v183
	v_pk_mul_f32 v[76:77], v[76:77], v[186:187] op_sel_hi:[1,0]
	v_pk_mul_f32 v[78:79], v[78:79], v[186:187] op_sel_hi:[1,0]
	v_pk_mul_f32 v[76:77], v[76:77], v[180:181]
	v_pk_mul_f32 v[78:79], v[78:79], v[182:183]
	v_pk_mul_f32 v[180:181], v[72:73], v[184:185] op_sel_hi:[1,0]
	v_pk_mul_f32 v[182:183], v[74:75], v[184:185] op_sel_hi:[1,0]
	v_pk_mul_f32 v[72:73], v[72:73], v[64:65]
	v_exp_f32_e32 v180, v180
	v_exp_f32_e32 v181, v181
	v_exp_f32_e32 v182, v182
	v_exp_f32_e32 v183, v183
	v_pk_mul_f32 v[74:75], v[74:75], v[66:67]
	v_pk_add_f32 v[180:181], v[180:181], v[188:189] op_sel_hi:[1,0]
	v_pk_add_f32 v[182:183], v[182:183], v[188:189] op_sel_hi:[1,0]
	v_rcp_f32_e32 v180, v180
	v_rcp_f32_e32 v181, v181
	v_rcp_f32_e32 v182, v182
	v_rcp_f32_e32 v183, v183
	v_pk_mul_f32 v[72:73], v[72:73], v[186:187] op_sel_hi:[1,0]
	v_pk_mul_f32 v[74:75], v[74:75], v[186:187] op_sel_hi:[1,0]
	v_pk_mul_f32 v[72:73], v[72:73], v[180:181]
	v_pk_mul_f32 v[74:75], v[74:75], v[182:183]
	v_cvt_pk_bf16_f32 v64, v76, v77
	v_cvt_pk_bf16_f32 v65, v78, v79
	v_cvt_pk_bf16_f32 v66, v72, v73
	v_cvt_pk_bf16_f32 v67, v74, v75
	s_nop 0
	global_store_dwordx4 v[80:81], v[64:67], off
	global_load_dword v64, v[150:151], off offset:512
	s_nop 0
	v_add_u32_e32 v65, 0x80, v144
	s_waitcnt vmcnt(0)
	v_fmamk_f32 v64, v64, 0x3a800000, v158
	v_mul_f32_e32 v66, 0x4b800000, v64
	v_cmp_gt_f32_e32 vcc, s77, v64
	s_nop 1
	v_cndmask_b32_e32 v64, v64, v66, vcc
	v_rsq_f32_e32 v66, v64
	v_mad_i64_i32 v[64:65], s[6:7], v65, s79, v[146:147]
	v_lshl_add_u64 v[64:65], v[64:65], 0, v[148:149]
	v_mul_f32_e32 v67, 0x45800000, v66
	v_cndmask_b32_e32 v66, v66, v67, vcc
	v_mul_f32_e32 v184, 0xbfb8aa3b, v66
	v_mul_f32_e32 v186, v66, v66
	v_pk_mul_f32 v[180:181], v[60:61], v[184:185] op_sel_hi:[1,0]
	v_pk_mul_f32 v[182:183], v[62:63], v[184:185] op_sel_hi:[1,0]
	v_pk_mul_f32 v[60:61], v[60:61], v[52:53]
	v_exp_f32_e32 v180, v180
	v_exp_f32_e32 v181, v181
	v_exp_f32_e32 v182, v182
	v_exp_f32_e32 v183, v183
	v_pk_mul_f32 v[62:63], v[62:63], v[54:55]
	v_pk_add_f32 v[180:181], v[180:181], v[188:189] op_sel_hi:[1,0]
	v_pk_add_f32 v[182:183], v[182:183], v[188:189] op_sel_hi:[1,0]
	v_rcp_f32_e32 v180, v180
	v_rcp_f32_e32 v181, v181
	v_rcp_f32_e32 v182, v182
	v_rcp_f32_e32 v183, v183
	v_pk_mul_f32 v[60:61], v[60:61], v[186:187] op_sel_hi:[1,0]
	v_pk_mul_f32 v[62:63], v[62:63], v[186:187] op_sel_hi:[1,0]
	v_pk_mul_f32 v[60:61], v[60:61], v[180:181]
	v_pk_mul_f32 v[62:63], v[62:63], v[182:183]
	v_pk_mul_f32 v[180:181], v[56:57], v[184:185] op_sel_hi:[1,0]
	v_pk_mul_f32 v[182:183], v[58:59], v[184:185] op_sel_hi:[1,0]
	v_pk_mul_f32 v[56:57], v[56:57], v[48:49]
	v_exp_f32_e32 v180, v180
	v_exp_f32_e32 v181, v181
	v_exp_f32_e32 v182, v182
	v_exp_f32_e32 v183, v183
	v_pk_mul_f32 v[58:59], v[58:59], v[50:51]
	v_pk_add_f32 v[180:181], v[180:181], v[188:189] op_sel_hi:[1,0]
	v_pk_add_f32 v[182:183], v[182:183], v[188:189] op_sel_hi:[1,0]
	v_rcp_f32_e32 v180, v180
	v_rcp_f32_e32 v181, v181
	v_rcp_f32_e32 v182, v182
	v_rcp_f32_e32 v183, v183
	v_pk_mul_f32 v[56:57], v[56:57], v[186:187] op_sel_hi:[1,0]
	v_pk_mul_f32 v[58:59], v[58:59], v[186:187] op_sel_hi:[1,0]
	v_pk_mul_f32 v[56:57], v[56:57], v[180:181]
	v_pk_mul_f32 v[58:59], v[58:59], v[182:183]
	v_cvt_pk_bf16_f32 v48, v60, v61
	v_cvt_pk_bf16_f32 v49, v62, v63
	v_cvt_pk_bf16_f32 v50, v56, v57
	v_cvt_pk_bf16_f32 v51, v58, v59
	s_nop 0
	global_store_dwordx4 v[64:65], v[48:51], off
	global_load_dword v48, v[150:151], off offset:576
	s_nop 0
	v_add_u32_e32 v49, 0x90, v144
	s_waitcnt vmcnt(0)
; __device__ __forceinline__ unsigned cvt_pk_bf16(float lo, float hi) { cvf32x2_t v = {lo, hi}; cvbf16x2_t b = __builtin_convertvector(v, cvbf16x2_t); return __builtin_bit_cast(unsigned, b); }
; __device__ __forceinline__ float fsigm(float x) { return __builtin_amdgcn_rcpf(1.f + __expf(-x)); }
; __device__ __forceinline__ float fsilu(float x) { return x * fsigm(x); }
; __device__ __forceinline__ float row_rs(const float* ssq, int row) { return ssq ? rsqrtf(ssq[row] * (1.f / 1024.f) + RMS_EPS) : 1.f; }
;     __device__ __forceinline__ void operator()(const f32x4 (&acc)[2][2][4][2], const Unit& u, int wr, int wc, int fr, int fq) const {
;         const int row0 = u.pm * BM + wr * 64 + fr, col0 = u.pn * HALF + wc * 32 + 8 * fq;
; #pragma unroll
;         for (int ai = 0; ai < 2; ++ai)
; #pragma unroll
;             for (int m = 0; m < 4; ++m) { const int row = row0 + ai * HALF + m * 16; const float rs = row_rs(ssq, row);
;                 u32x4 w; unsigned pk[4];
; #pragma unroll
;                 for (int n = 0; n < 2; ++n) { const f32x4 g = acc[ai][0][m][n] * rs, up = acc[ai][1][m][n] * rs;
;                     pk[2 * n] = cvt_pk_bf16(fsilu(g[0]) * up[0], fsilu(g[1]) * up[1]); pk[2 * n + 1] = cvt_pk_bf16(fsilu(g[2]) * up[2], fsilu(g[3]) * up[3]); }
;                 w.x = pk[0]; w.y = pk[1]; w.z = pk[2]; w.w = pk[3];
;                 st_wt16(H + (size_t)row * ldh + col0, w); }
	v_fmamk_f32 v48, v48, 0x3a800000, v158
	v_mul_f32_e32 v50, 0x4b800000, v48
	v_cmp_gt_f32_e32 vcc, s77, v48
	s_nop 1
	v_cndmask_b32_e32 v48, v48, v50, vcc
	v_rsq_f32_e32 v50, v48
	v_mad_i64_i32 v[48:49], s[6:7], v49, s79, v[146:147]
	v_lshl_add_u64 v[48:49], v[48:49], 0, v[148:149]
	v_mul_f32_e32 v51, 0x45800000, v50
	v_cndmask_b32_e32 v50, v50, v51, vcc
	v_mul_f32_e32 v184, 0xbfb8aa3b, v50
	v_mul_f32_e32 v186, v50, v50
	v_pk_mul_f32 v[180:181], v[44:45], v[184:185] op_sel_hi:[1,0]
	v_pk_mul_f32 v[182:183], v[46:47], v[184:185] op_sel_hi:[1,0]
	v_pk_mul_f32 v[44:45], v[44:45], v[36:37]
	v_exp_f32_e32 v180, v180
	v_exp_f32_e32 v181, v181
	v_exp_f32_e32 v182, v182
	v_exp_f32_e32 v183, v183
	v_pk_mul_f32 v[46:47], v[46:47], v[38:39]
	v_pk_add_f32 v[180:181], v[180:181], v[188:189] op_sel_hi:[1,0]
	v_pk_add_f32 v[182:183], v[182:183], v[188:189] op_sel_hi:[1,0]
	v_rcp_f32_e32 v180, v180
	v_rcp_f32_e32 v181, v181
	v_rcp_f32_e32 v182, v182
	v_rcp_f32_e32 v183, v183
	v_pk_mul_f32 v[44:45], v[44:45], v[186:187] op_sel_hi:[1,0]
	v_pk_mul_f32 v[46:47], v[46:47], v[186:187] op_sel_hi:[1,0]
	v_pk_mul_f32 v[44:45], v[44:45], v[180:181]
	v_pk_mul_f32 v[46:47], v[46:47], v[182:183]
	v_pk_mul_f32 v[180:181], v[40:41], v[184:185] op_sel_hi:[1,0]
	v_pk_mul_f32 v[182:183], v[42:43], v[184:185] op_sel_hi:[1,0]
	v_pk_mul_f32 v[40:41], v[40:41], v[32:33]
	v_exp_f32_e32 v180, v180
	v_exp_f32_e32 v181, v181
	v_exp_f32_e32 v182, v182
	v_exp_f32_e32 v183, v183
	v_pk_mul_f32 v[42:43], v[42:43], v[34:35]
	v_pk_add_f32 v[180:181], v[180:181], v[188:189] op_sel_hi:[1,0]
	v_pk_add_f32 v[182:183], v[182:183], v[188:189] op_sel_hi:[1,0]
	v_rcp_f32_e32 v180, v180
	v_rcp_f32_e32 v181, v181
	v_rcp_f32_e32 v182, v182
	v_rcp_f32_e32 v183, v183
	v_pk_mul_f32 v[40:41], v[40:41], v[186:187] op_sel_hi:[1,0]
	v_pk_mul_f32 v[42:43], v[42:43], v[186:187] op_sel_hi:[1,0]
	v_pk_mul_f32 v[40:41], v[40:41], v[180:181]
	v_pk_mul_f32 v[42:43], v[42:43], v[182:183]
	v_cvt_pk_bf16_f32 v32, v44, v45
	v_cvt_pk_bf16_f32 v33, v46, v47
	v_cvt_pk_bf16_f32 v34, v40, v41
	v_cvt_pk_bf16_f32 v35, v42, v43
	s_nop 0
	global_store_dwordx4 v[48:49], v[32:35], off
	global_load_dword v32, v[150:151], off offset:640
	s_nop 0
	v_add_u32_e32 v33, 0xa0, v144
	s_waitcnt vmcnt(0)
	v_fmamk_f32 v32, v32, 0x3a800000, v158
	v_mul_f32_e32 v34, 0x4b800000, v32
	v_cmp_gt_f32_e32 vcc, s77, v32
	s_nop 1
	v_cndmask_b32_e32 v32, v32, v34, vcc
	v_rsq_f32_e32 v34, v32
	v_mad_i64_i32 v[32:33], s[6:7], v33, s79, v[146:147]
	v_lshl_add_u64 v[32:33], v[32:33], 0, v[148:149]
	v_mul_f32_e32 v35, 0x45800000, v34
	v_cndmask_b32_e32 v34, v34, v35, vcc
	v_mul_f32_e32 v184, 0xbfb8aa3b, v34
	v_mul_f32_e32 v186, v34, v34
	v_pk_mul_f32 v[180:181], v[28:29], v[184:185] op_sel_hi:[1,0]
	v_pk_mul_f32 v[182:183], v[30:31], v[184:185] op_sel_hi:[1,0]
	v_pk_mul_f32 v[28:29], v[28:29], v[20:21]
	v_exp_f32_e32 v180, v180
	v_exp_f32_e32 v181, v181
	v_exp_f32_e32 v182, v182
	v_exp_f32_e32 v183, v183
	v_pk_mul_f32 v[30:31], v[30:31], v[22:23]
	v_pk_add_f32 v[180:181], v[180:181], v[188:189] op_sel_hi:[1,0]
	v_pk_add_f32 v[182:183], v[182:183], v[188:189] op_sel_hi:[1,0]
	v_rcp_f32_e32 v180, v180
	v_rcp_f32_e32 v181, v181
	v_rcp_f32_e32 v182, v182
	v_rcp_f32_e32 v183, v183
	v_pk_mul_f32 v[28:29], v[28:29], v[186:187] op_sel_hi:[1,0]
	v_pk_mul_f32 v[30:31], v[30:31], v[186:187] op_sel_hi:[1,0]
	v_pk_mul_f32 v[28:29], v[28:29], v[180:181]
	v_pk_mul_f32 v[30:31], v[30:31], v[182:183]
	v_pk_mul_f32 v[180:181], v[24:25], v[184:185] op_sel_hi:[1,0]
	v_pk_mul_f32 v[182:183], v[26:27], v[184:185] op_sel_hi:[1,0]
	v_pk_mul_f32 v[24:25], v[24:25], v[16:17]
	v_exp_f32_e32 v180, v180
	v_exp_f32_e32 v181, v181
	v_exp_f32_e32 v182, v182
	v_exp_f32_e32 v183, v183
	v_pk_mul_f32 v[26:27], v[26:27], v[18:19]
	v_pk_add_f32 v[180:181], v[180:181], v[188:189] op_sel_hi:[1,0]
	v_pk_add_f32 v[182:183], v[182:183], v[188:189] op_sel_hi:[1,0]
	v_rcp_f32_e32 v180, v180
	v_rcp_f32_e32 v181, v181
	v_rcp_f32_e32 v182, v182
	v_rcp_f32_e32 v183, v183
	v_pk_mul_f32 v[24:25], v[24:25], v[186:187] op_sel_hi:[1,0]
	v_pk_mul_f32 v[26:27], v[26:27], v[186:187] op_sel_hi:[1,0]
	v_pk_mul_f32 v[24:25], v[24:25], v[180:181]
	v_pk_mul_f32 v[26:27], v[26:27], v[182:183]
	v_cvt_pk_bf16_f32 v16, v28, v29
	v_cvt_pk_bf16_f32 v17, v30, v31
	v_cvt_pk_bf16_f32 v18, v24, v25
	v_cvt_pk_bf16_f32 v19, v26, v27
	s_nop 0
	global_store_dwordx4 v[32:33], v[16:19], off
	global_load_dword v16, v[150:151], off offset:704
	s_andn2_b64 vcc, exec, s[4:5]
	v_add_u32_e32 v17, 0xb0, v144
	s_mov_b64 s[4:5], -1
	s_waitcnt vmcnt(0)
	v_fmamk_f32 v16, v16, 0x3a800000, v158
	v_mul_f32_e32 v18, 0x4b800000, v16
	v_cmp_gt_f32_e64 s[6:7], s77, v16
	s_nop 1
	v_cndmask_b32_e64 v16, v16, v18, s[6:7]
	v_rsq_f32_e32 v18, v16
	v_mad_i64_i32 v[16:17], s[34:35], v17, s79, v[146:147]
	v_lshl_add_u64 v[16:17], v[16:17], 0, v[148:149]
	v_mul_f32_e32 v19, 0x45800000, v18
	v_cndmask_b32_e64 v18, v18, v19, s[6:7]
	v_mul_f32_e32 v184, 0xbfb8aa3b, v18
	v_mul_f32_e32 v186, v18, v18
	v_pk_mul_f32 v[180:181], v[12:13], v[184:185] op_sel_hi:[1,0]
	v_pk_mul_f32 v[182:183], v[14:15], v[184:185] op_sel_hi:[1,0]
	v_pk_mul_f32 v[12:13], v[12:13], v[4:5]
	v_exp_f32_e32 v180, v180
	v_exp_f32_e32 v181, v181
	v_exp_f32_e32 v182, v182
	v_exp_f32_e32 v183, v183
	v_pk_mul_f32 v[14:15], v[14:15], v[6:7]
	v_pk_add_f32 v[180:181], v[180:181], v[188:189] op_sel_hi:[1,0]
	v_pk_add_f32 v[182:183], v[182:183], v[188:189] op_sel_hi:[1,0]
	v_rcp_f32_e32 v180, v180
	v_rcp_f32_e32 v181, v181
	v_rcp_f32_e32 v182, v182
	v_rcp_f32_e32 v183, v183
	v_pk_mul_f32 v[12:13], v[12:13], v[186:187] op_sel_hi:[1,0]
	v_pk_mul_f32 v[14:15], v[14:15], v[186:187] op_sel_hi:[1,0]
	v_pk_mul_f32 v[12:13], v[12:13], v[180:181]
	v_pk_mul_f32 v[14:15], v[14:15], v[182:183]
	v_pk_mul_f32 v[180:181], v[8:9], v[184:185] op_sel_hi:[1,0]
	v_pk_mul_f32 v[182:183], v[10:11], v[184:185] op_sel_hi:[1,0]
	v_pk_mul_f32 v[8:9], v[8:9], v[0:1]
	v_exp_f32_e32 v180, v180
	v_exp_f32_e32 v181, v181
	v_exp_f32_e32 v182, v182
	v_exp_f32_e32 v183, v183
	v_pk_mul_f32 v[10:11], v[10:11], v[2:3]
	v_pk_add_f32 v[180:181], v[180:181], v[188:189] op_sel_hi:[1,0]
	v_pk_add_f32 v[182:183], v[182:183], v[188:189] op_sel_hi:[1,0]
	v_rcp_f32_e32 v180, v180
	v_rcp_f32_e32 v181, v181
	v_rcp_f32_e32 v182, v182
	v_rcp_f32_e32 v183, v183
	v_pk_mul_f32 v[8:9], v[8:9], v[186:187] op_sel_hi:[1,0]
	v_pk_mul_f32 v[10:11], v[10:11], v[186:187] op_sel_hi:[1,0]
	v_pk_mul_f32 v[8:9], v[8:9], v[180:181]
	v_pk_mul_f32 v[10:11], v[10:11], v[182:183]
	v_cvt_pk_bf16_f32 v0, v12, v13
	v_cvt_pk_bf16_f32 v1, v14, v15
	v_cvt_pk_bf16_f32 v2, v8, v9
	v_cvt_pk_bf16_f32 v3, v10, v11
	s_nop 0
	global_store_dwordx4 v[16:17], v[0:3], off
	s_cbranch_vccnz .LBB0_1267
	s_andn2_b64 vcc, exec, s[10:11]
	s_cbranch_vccnz .LBB0_1266
	s_barrier
	s_branch .LBB0_1266
